# P7: first K iteration peeled, first-touch MFMAs take 0 as accumulator: no accumulator zeroing per unit
# speedup vs baseline: 1.0138x; 1.0071x over previous
.LBB0_955:
	s_ashr_i32 s13, s12, 31
	s_lshl_b64 s[14:15], s[12:13], 19
	s_add_u32 s14, s26, s14
	s_addc_u32 s15, s27, s15
	s_and_b64 s[16:17], s[2:3], exec
	s_cselect_b32 s13, s15, s21
	s_cselect_b32 s38, s14, s20
	s_ashr_i32 s11, s10, 31
	s_lshl_b64 s[16:17], s[10:11], 19
	s_add_u32 s16, s28, s16
	s_addc_u32 s17, s29, s17
	s_and_b64 s[24:25], s[2:3], exec
	s_cselect_b32 s11, s17, s23
	s_cselect_b32 s39, s16, s22
	s_add_u32 s20, s20, 0x40080
	s_addc_u32 s21, s21, 0
	s_add_u32 s51, s22, 0x100
	s_addc_u32 s52, s23, 0
	s_mov_b32 s53, -2
	ds_read_b128 v[154:157], v150
	ds_read_b128 v[158:161], v150 offset:1024
	ds_read_b128 v[166:169], v150 offset:2048
	ds_read_b128 v[170:173], v150 offset:3072
	ds_read_b128 v[174:177], v151
	ds_read_b128 v[178:181], v151 offset:1024
	ds_read_b128 v[182:185], v151 offset:2048
	ds_read_b128 v[186:189], v151 offset:3072
	s_add_u32 s22, s20, 0xfffc0080
	s_addc_u32 s23, s21, -1
	s_cmp_eq_u32 s53, 12
	s_cselect_b32 s25, s13, s23
	s_cselect_b32 s24, s38, s22
	s_cselect_b32 s23, s11, s52
	s_cselect_b32 s22, s39, s51
	v_lshl_add_u64 v[146:147], s[20:21], 0, v[138:139]
	s_add_i32 m0, s35, 0xc000
	ds_read_b128 v[190:193], v152
	ds_read_b128 v[194:197], v152 offset:1024
	ds_read_b128 v[198:201], v152 offset:2048
	ds_read_b128 v[202:205], v152 offset:3072
	ds_read_b128 v[206:209], v152 offset:4096
	ds_read_b128 v[210:213], v152 offset:5120
	ds_read_b128 v[214:217], v152 offset:6144
	ds_read_b128 v[218:221], v152 offset:7168
	global_load_lds_dwordx4 v[146:147], off
	v_lshl_add_u64 v[146:147], s[20:21], 0, v[140:141]
	s_add_i32 m0, s35, 0xe000
	s_nop 0
	global_load_lds_dwordx4 v[146:147], off
	s_waitcnt vmcnt(8)
	s_waitcnt lgkmcnt(0)
	s_setprio 1
	s_barrier
	v_mfma_f32_16x16x32_bf16 v[124:127], v[154:157], v[190:193], 0
	v_mfma_f32_16x16x32_bf16 v[120:123], v[166:169], v[190:193], 0
	v_mfma_f32_16x16x32_bf16 v[108:111], v[154:157], v[198:201], 0
	v_mfma_f32_16x16x32_bf16 v[104:107], v[166:169], v[198:201], 0
	v_mfma_f32_16x16x32_bf16 v[92:95], v[154:157], v[206:209], 0
	v_mfma_f32_16x16x32_bf16 v[88:91], v[166:169], v[206:209], 0
	v_mfma_f32_16x16x32_bf16 v[76:79], v[154:157], v[214:217], 0
	v_mfma_f32_16x16x32_bf16 v[72:75], v[166:169], v[214:217], 0
	v_mfma_f32_16x16x32_bf16 v[124:127], v[158:161], v[194:197], v[124:127]
	v_mfma_f32_16x16x32_bf16 v[120:123], v[170:173], v[194:197], v[120:123]
	v_mfma_f32_16x16x32_bf16 v[108:111], v[158:161], v[202:205], v[108:111]
	v_mfma_f32_16x16x32_bf16 v[104:107], v[170:173], v[202:205], v[104:107]
	v_mfma_f32_16x16x32_bf16 v[92:95], v[158:161], v[210:213], v[92:95]
	v_mfma_f32_16x16x32_bf16 v[88:91], v[170:173], v[210:213], v[88:91]
	v_mfma_f32_16x16x32_bf16 v[76:79], v[158:161], v[218:221], v[76:79]
	v_mfma_f32_16x16x32_bf16 v[72:75], v[170:173], v[218:221], v[72:75]
	v_mfma_f32_16x16x32_bf16 v[116:119], v[174:177], v[190:193], 0
	v_mfma_f32_16x16x32_bf16 v[112:115], v[182:185], v[190:193], 0
	v_mfma_f32_16x16x32_bf16 v[100:103], v[174:177], v[198:201], 0
	v_mfma_f32_16x16x32_bf16 v[96:99], v[182:185], v[198:201], 0
	v_mfma_f32_16x16x32_bf16 v[84:87], v[174:177], v[206:209], 0
	v_mfma_f32_16x16x32_bf16 v[80:83], v[182:185], v[206:209], 0
	v_mfma_f32_16x16x32_bf16 v[68:71], v[174:177], v[214:217], 0
	v_mfma_f32_16x16x32_bf16 v[64:67], v[182:185], v[214:217], 0
	v_mfma_f32_16x16x32_bf16 v[116:119], v[178:181], v[194:197], v[116:119]
	v_mfma_f32_16x16x32_bf16 v[112:115], v[186:189], v[194:197], v[112:115]
	v_mfma_f32_16x16x32_bf16 v[100:103], v[178:181], v[202:205], v[100:103]
	v_mfma_f32_16x16x32_bf16 v[96:99], v[186:189], v[202:205], v[96:99]
	v_mfma_f32_16x16x32_bf16 v[84:87], v[178:181], v[210:213], v[84:87]
	v_mfma_f32_16x16x32_bf16 v[80:83], v[186:189], v[210:213], v[80:83]
	v_mfma_f32_16x16x32_bf16 v[68:71], v[178:181], v[218:221], v[68:71]
	v_mfma_f32_16x16x32_bf16 v[64:67], v[186:189], v[218:221], v[64:67]
	s_barrier
	s_setprio 0
	s_add_i32 s54, s49, s30
	v_lshl_add_u64 v[146:147], s[22:23], 0, v[132:133]
	s_mov_b32 m0, s54
	ds_read_b128 v[190:193], v152 offset:16384
	ds_read_b128 v[194:197], v152 offset:17408
	ds_read_b128 v[198:201], v152 offset:18432
	ds_read_b128 v[202:205], v152 offset:19456
	ds_read_b128 v[206:209], v152 offset:20480
	ds_read_b128 v[210:213], v152 offset:21504
	ds_read_b128 v[214:217], v152 offset:22528
	ds_read_b128 v[218:221], v152 offset:23552
	global_load_lds_dwordx4 v[146:147], off
	s_add_i32 m0, s54, 0x2000
	s_add_u32 s54, s22, 0x40000
	v_lshl_add_u64 v[162:163], s[22:23], 0, v[128:129]
	s_addc_u32 s55, s23, 0
	s_add_i32 s56, s50, s30
	global_load_lds_dwordx4 v[162:163], off
	v_lshl_add_u64 v[222:223], s[54:55], 0, v[132:133]
	s_mov_b32 m0, s56
	v_lshl_add_u64 v[224:225], s[24:25], 0, v[130:131]
	global_load_lds_dwordx4 v[222:223], off
	v_lshl_add_u64 v[222:223], s[54:55], 0, v[128:129]
	s_add_i32 m0, s56, 0x2000
	s_nop 0
	global_load_lds_dwordx4 v[222:223], off
	v_lshl_add_u64 v[222:223], s[24:25], 0, v[134:135]
	s_mov_b32 m0, s35
	s_nop 0
	global_load_lds_dwordx4 v[222:223], off
	s_mov_b32 m0, s36
	s_nop 0
	global_load_lds_dwordx4 v[224:225], off
	s_waitcnt vmcnt(8)
	s_waitcnt lgkmcnt(0)
	s_setprio 1
	s_barrier
	v_mfma_f32_16x16x32_bf16 v[60:63], v[154:157], v[190:193], 0
	v_mfma_f32_16x16x32_bf16 v[56:59], v[166:169], v[190:193], 0
	v_mfma_f32_16x16x32_bf16 v[44:47], v[154:157], v[198:201], 0
	v_mfma_f32_16x16x32_bf16 v[40:43], v[166:169], v[198:201], 0
	v_mfma_f32_16x16x32_bf16 v[28:31], v[154:157], v[206:209], 0
	v_mfma_f32_16x16x32_bf16 v[24:27], v[166:169], v[206:209], 0
	v_mfma_f32_16x16x32_bf16 v[12:15], v[154:157], v[214:217], 0
	v_mfma_f32_16x16x32_bf16 v[8:11], v[166:169], v[214:217], 0
	v_mfma_f32_16x16x32_bf16 v[60:63], v[158:161], v[194:197], v[60:63]
	v_mfma_f32_16x16x32_bf16 v[56:59], v[170:173], v[194:197], v[56:59]
	v_mfma_f32_16x16x32_bf16 v[44:47], v[158:161], v[202:205], v[44:47]
	v_mfma_f32_16x16x32_bf16 v[40:43], v[170:173], v[202:205], v[40:43]
	v_mfma_f32_16x16x32_bf16 v[28:31], v[158:161], v[210:213], v[28:31]
	v_mfma_f32_16x16x32_bf16 v[24:27], v[170:173], v[210:213], v[24:27]
	v_mfma_f32_16x16x32_bf16 v[12:15], v[158:161], v[218:221], v[12:15]
	v_mfma_f32_16x16x32_bf16 v[8:11], v[170:173], v[218:221], v[8:11]
	v_mfma_f32_16x16x32_bf16 v[52:55], v[174:177], v[190:193], 0
	v_mfma_f32_16x16x32_bf16 v[48:51], v[182:185], v[190:193], 0
	v_mfma_f32_16x16x32_bf16 v[36:39], v[174:177], v[198:201], 0
	v_mfma_f32_16x16x32_bf16 v[32:35], v[182:185], v[198:201], 0
	v_mfma_f32_16x16x32_bf16 v[20:23], v[174:177], v[206:209], 0
	v_mfma_f32_16x16x32_bf16 v[16:19], v[182:185], v[206:209], 0
	v_mfma_f32_16x16x32_bf16 v[4:7], v[174:177], v[214:217], 0
	v_mfma_f32_16x16x32_bf16 v[0:3], v[182:185], v[214:217], 0
	v_mfma_f32_16x16x32_bf16 v[52:55], v[178:181], v[194:197], v[52:55]
	v_mfma_f32_16x16x32_bf16 v[48:51], v[186:189], v[194:197], v[48:51]
	v_mfma_f32_16x16x32_bf16 v[36:39], v[178:181], v[202:205], v[36:39]
	v_mfma_f32_16x16x32_bf16 v[32:35], v[186:189], v[202:205], v[32:35]
	v_mfma_f32_16x16x32_bf16 v[20:23], v[178:181], v[210:213], v[20:23]
	v_mfma_f32_16x16x32_bf16 v[16:19], v[186:189], v[210:213], v[16:19]
	v_mfma_f32_16x16x32_bf16 v[4:7], v[178:181], v[218:221], v[4:7]
	v_mfma_f32_16x16x32_bf16 v[0:3], v[186:189], v[218:221], v[0:3]
	s_barrier
	s_setprio 0
	s_add_i32 s54, 0, 0x18000
	v_add_u32_e32 v153, s54, v149
	s_add_i32 s55, 0, 0x1c000
	ds_read_b128 v[154:157], v153
	ds_read_b128 v[158:161], v153 offset:1024
	ds_read_b128 v[166:169], v153 offset:2048
	ds_read_b128 v[170:173], v153 offset:3072
	v_add_u32_e32 v153, s55, v149
	ds_read_b128 v[174:177], v153
	ds_read_b128 v[178:181], v153 offset:1024
	ds_read_b128 v[182:185], v153 offset:2048
	ds_read_b128 v[186:189], v153 offset:3072
	s_add_u32 s24, s24, 0x40000
	s_addc_u32 s25, s25, 0
	s_mov_b32 m0, s37
	v_lshl_add_u64 v[226:227], s[24:25], 0, v[134:135]
	ds_read_b128 v[190:193], v152 offset:32768
	ds_read_b128 v[194:197], v152 offset:33792
	ds_read_b128 v[198:201], v152 offset:34816
	ds_read_b128 v[202:205], v152 offset:35840
	ds_read_b128 v[206:209], v152 offset:36864
	ds_read_b128 v[210:213], v152 offset:37888
	ds_read_b128 v[214:217], v152 offset:38912
	ds_read_b128 v[218:221], v152 offset:39936
	global_load_lds_dwordx4 v[226:227], off
	v_lshl_add_u64 v[226:227], s[24:25], 0, v[130:131]
	s_mov_b32 m0, s40
	s_nop 0
	global_load_lds_dwordx4 v[226:227], off
	s_waitcnt vmcnt(8)
	s_waitcnt lgkmcnt(0)
	s_setprio 1
	s_barrier
	v_mfma_f32_16x16x32_bf16 v[124:127], v[154:157], v[190:193], v[124:127]
	v_mfma_f32_16x16x32_bf16 v[120:123], v[166:169], v[190:193], v[120:123]
	v_mfma_f32_16x16x32_bf16 v[108:111], v[154:157], v[198:201], v[108:111]
	v_mfma_f32_16x16x32_bf16 v[104:107], v[166:169], v[198:201], v[104:107]
	v_mfma_f32_16x16x32_bf16 v[92:95], v[154:157], v[206:209], v[92:95]
	v_mfma_f32_16x16x32_bf16 v[88:91], v[166:169], v[206:209], v[88:91]
	v_mfma_f32_16x16x32_bf16 v[76:79], v[154:157], v[214:217], v[76:79]
	v_mfma_f32_16x16x32_bf16 v[72:75], v[166:169], v[214:217], v[72:75]
	v_mfma_f32_16x16x32_bf16 v[124:127], v[158:161], v[194:197], v[124:127]
	v_mfma_f32_16x16x32_bf16 v[120:123], v[170:173], v[194:197], v[120:123]
	v_mfma_f32_16x16x32_bf16 v[108:111], v[158:161], v[202:205], v[108:111]
	v_mfma_f32_16x16x32_bf16 v[104:107], v[170:173], v[202:205], v[104:107]
	v_mfma_f32_16x16x32_bf16 v[92:95], v[158:161], v[210:213], v[92:95]
	v_mfma_f32_16x16x32_bf16 v[88:91], v[170:173], v[210:213], v[88:91]
	v_mfma_f32_16x16x32_bf16 v[76:79], v[158:161], v[218:221], v[76:79]
	v_mfma_f32_16x16x32_bf16 v[72:75], v[170:173], v[218:221], v[72:75]
	v_mfma_f32_16x16x32_bf16 v[116:119], v[174:177], v[190:193], v[116:119]
	v_mfma_f32_16x16x32_bf16 v[112:115], v[182:185], v[190:193], v[112:115]
	v_mfma_f32_16x16x32_bf16 v[100:103], v[174:177], v[198:201], v[100:103]
	v_mfma_f32_16x16x32_bf16 v[96:99], v[182:185], v[198:201], v[96:99]
	v_mfma_f32_16x16x32_bf16 v[84:87], v[174:177], v[206:209], v[84:87]
	v_mfma_f32_16x16x32_bf16 v[80:83], v[182:185], v[206:209], v[80:83]
	v_mfma_f32_16x16x32_bf16 v[68:71], v[174:177], v[214:217], v[68:71]
	v_mfma_f32_16x16x32_bf16 v[64:67], v[182:185], v[214:217], v[64:67]
	v_mfma_f32_16x16x32_bf16 v[116:119], v[178:181], v[194:197], v[116:119]
	v_mfma_f32_16x16x32_bf16 v[112:115], v[186:189], v[194:197], v[112:115]
	v_mfma_f32_16x16x32_bf16 v[100:103], v[178:181], v[202:205], v[100:103]
	v_mfma_f32_16x16x32_bf16 v[96:99], v[186:189], v[202:205], v[96:99]
	v_mfma_f32_16x16x32_bf16 v[84:87], v[178:181], v[210:213], v[84:87]
	v_mfma_f32_16x16x32_bf16 v[80:83], v[186:189], v[210:213], v[80:83]
	v_mfma_f32_16x16x32_bf16 v[68:71], v[178:181], v[218:221], v[68:71]
	v_mfma_f32_16x16x32_bf16 v[64:67], v[186:189], v[218:221], v[64:67]
	s_barrier
	s_setprio 0
	s_add_i32 s24, s54, s30
	v_lshl_add_u64 v[146:147], v[146:147], 0, s[6:7]
	s_mov_b32 m0, s24
	ds_read_b128 v[190:193], v152 offset:49152
	ds_read_b128 v[194:197], v152 offset:50176
	ds_read_b128 v[198:201], v152 offset:51200
	ds_read_b128 v[202:205], v152 offset:52224
	ds_read_b128 v[206:209], v152 offset:53248
	ds_read_b128 v[210:213], v152 offset:54272
	ds_read_b128 v[214:217], v152 offset:55296
	ds_read_b128 v[218:221], v152 offset:56320
	global_load_lds_dwordx4 v[146:147], off
	s_add_i32 m0, s24, 0x2000
	s_add_u32 s22, s22, 0x40080
	v_lshl_add_u64 v[146:147], v[162:163], 0, s[6:7]
	s_addc_u32 s23, s23, 0
	s_add_i32 s24, s55, s30
	global_load_lds_dwordx4 v[146:147], off
	v_lshl_add_u64 v[146:147], s[22:23], 0, v[132:133]
	s_mov_b32 m0, s24
	s_nop 0
	global_load_lds_dwordx4 v[146:147], off
	v_lshl_add_u64 v[146:147], s[22:23], 0, v[128:129]
	s_add_i32 m0, s24, 0x2000
	s_nop 0
	global_load_lds_dwordx4 v[146:147], off
	v_lshl_add_u64 v[146:147], v[222:223], 0, s[6:7]
	s_mov_b32 m0, s45
	s_nop 0
	global_load_lds_dwordx4 v[146:147], off
	v_lshl_add_u64 v[146:147], v[224:225], 0, s[6:7]
	s_mov_b32 m0, s46
	s_nop 0
	global_load_lds_dwordx4 v[146:147], off
	s_waitcnt vmcnt(8)
	s_waitcnt lgkmcnt(0)
	s_setprio 1
	s_barrier
	v_mfma_f32_16x16x32_bf16 v[60:63], v[154:157], v[190:193], v[60:63]
	v_mfma_f32_16x16x32_bf16 v[56:59], v[166:169], v[190:193], v[56:59]
	v_mfma_f32_16x16x32_bf16 v[44:47], v[154:157], v[198:201], v[44:47]
	v_mfma_f32_16x16x32_bf16 v[40:43], v[166:169], v[198:201], v[40:43]
	v_mfma_f32_16x16x32_bf16 v[28:31], v[154:157], v[206:209], v[28:31]
	v_mfma_f32_16x16x32_bf16 v[24:27], v[166:169], v[206:209], v[24:27]
	v_mfma_f32_16x16x32_bf16 v[12:15], v[154:157], v[214:217], v[12:15]
	v_mfma_f32_16x16x32_bf16 v[8:11], v[166:169], v[214:217], v[8:11]
	v_mfma_f32_16x16x32_bf16 v[60:63], v[158:161], v[194:197], v[60:63]
	v_mfma_f32_16x16x32_bf16 v[56:59], v[170:173], v[194:197], v[56:59]
	v_mfma_f32_16x16x32_bf16 v[44:47], v[158:161], v[202:205], v[44:47]
	v_mfma_f32_16x16x32_bf16 v[40:43], v[170:173], v[202:205], v[40:43]
	v_mfma_f32_16x16x32_bf16 v[28:31], v[158:161], v[210:213], v[28:31]
	v_mfma_f32_16x16x32_bf16 v[24:27], v[170:173], v[210:213], v[24:27]
	v_mfma_f32_16x16x32_bf16 v[12:15], v[158:161], v[218:221], v[12:15]
	v_mfma_f32_16x16x32_bf16 v[8:11], v[170:173], v[218:221], v[8:11]
	v_mfma_f32_16x16x32_bf16 v[52:55], v[174:177], v[190:193], v[52:55]
	v_mfma_f32_16x16x32_bf16 v[48:51], v[182:185], v[190:193], v[48:51]
	v_mfma_f32_16x16x32_bf16 v[36:39], v[174:177], v[198:201], v[36:39]
	v_mfma_f32_16x16x32_bf16 v[32:35], v[182:185], v[198:201], v[32:35]
	v_mfma_f32_16x16x32_bf16 v[20:23], v[174:177], v[206:209], v[20:23]
	v_mfma_f32_16x16x32_bf16 v[16:19], v[182:185], v[206:209], v[16:19]
	v_mfma_f32_16x16x32_bf16 v[4:7], v[174:177], v[214:217], v[4:7]
	v_mfma_f32_16x16x32_bf16 v[0:3], v[182:185], v[214:217], v[0:3]
	v_mfma_f32_16x16x32_bf16 v[52:55], v[178:181], v[194:197], v[52:55]
	v_mfma_f32_16x16x32_bf16 v[48:51], v[186:189], v[194:197], v[48:51]
	v_mfma_f32_16x16x32_bf16 v[36:39], v[178:181], v[202:205], v[36:39]
	v_mfma_f32_16x16x32_bf16 v[32:35], v[186:189], v[202:205], v[32:35]
	v_mfma_f32_16x16x32_bf16 v[20:23], v[178:181], v[210:213], v[20:23]
	v_mfma_f32_16x16x32_bf16 v[16:19], v[186:189], v[210:213], v[16:19]
	v_mfma_f32_16x16x32_bf16 v[4:7], v[178:181], v[218:221], v[4:7]
	v_mfma_f32_16x16x32_bf16 v[0:3], v[186:189], v[218:221], v[0:3]
	s_barrier
	s_setprio 0
	s_add_i32 s53, s53, 2
	s_add_u32 s20, s20, 0x100
	s_addc_u32 s21, s21, 0
	s_add_u32 s51, s51, 0x100
	s_addc_u32 s52, s52, 0
	s_cmp_gt_u32 s53, 13
	s_cbranch_scc0 .LBB0_956
	s_branch .Lpeel_exit_p7

.Lpeel_exit_p7:
	s_and_b64 vcc, exec, s[8:9]
	s_cbranch_vccz .LBB0_959
	s_barrier
